# v10 with priority 1 held from PV through tail, barrier, top and QK (only softmax at 0)
# speedup vs baseline: 1.0120x; 1.0120x over previous
; #define SBAR() __builtin_amdgcn_sched_barrier(0)
; template <int DQK, int MODE, bool PIPE>
; DI void attn_core(const u16* __restrict__ Qg, const u16* __restrict__ Kg, const u16* __restrict__ Vtg, int ntiles,
;                   int kr_lo, int rs, int r_q, int c_q, int cs, const float* biasL, char* lds, f32x16 (&o)[4], float& l_out, int tid) {
;     ...
;     for (int i = 0; i < 16; ++i) { p0[i] = __builtin_amdgcn_exp2f(p0[i]); p1[i] = __builtin_amdgcn_exp2f(p1[i]); ps += p0[i] + p1[i]; }
;     l += ps;
;     const char* vb = lds + (t & 1) * A_BUF + A_VOFF + r32 * 136 + h * 8;
;     {
;       bf16x8 pfc;
;       constexpr int R = PV_RING;
;       const unsigned vaddr = (unsigned)(size_t)vb;
;       s16x4 vlo[R], vhi[R];
;       SBAR();
;       vlo[0] = lds_rd64<0>(vaddr); vhi[0] = lds_rd64<16>(vaddr);
;       vlo[1] = lds_rd64<32 * 136>(vaddr); vhi[1] = lds_rd64<32 * 136 + 16>(vaddr);
;       if (R > 2) { vlo[2 % R] = lds_rd64<64 * 136>(vaddr); vhi[2 % R] = lds_rd64<64 * 136 + 16>(vaddr); }
;       if (R > 3) { vlo[3 % R] = lds_rd64<96 * 136>(vaddr); vhi[3 % R] = lds_rd64<96 * 136 + 16>(vaddr); }
;       SBAR();
;       __builtin_amdgcn_s_setprio(1);
;       PvStep<0, 16, R>::run(vaddr, vlo, vhi, p0, p1, pfc, o);
;       __builtin_amdgcn_s_setprio(0);
;     ...
;       if (t + 2 < ntiles) swriteK(t & 1);
;       if (t + 3 < ntiles) gloadK(t + 3);
;     } else {
;       if (is_active(t)) { qk(t, c0, c1); sm_pv(t, c0, c1); }
;       if (t + 1 < ntiles) swriteK((t + 1) & 1);
;       if (t + 2 < ntiles) gloadK(t + 2);
.LBB0_825:
	v_exp_f32_e32 v66, v66
	v_exp_f32_e32 v82, v82
	v_exp_f32_e32 v67, v67
	v_exp_f32_e32 v83, v83
	v_exp_f32_e32 v68, v68
	v_exp_f32_e32 v84, v84
	v_exp_f32_e32 v69, v69
	v_exp_f32_e32 v85, v85
	v_exp_f32_e32 v70, v70
	v_exp_f32_e32 v86, v86
	v_exp_f32_e32 v71, v71
	v_exp_f32_e32 v87, v87
	v_exp_f32_e32 v72, v72
	v_exp_f32_e32 v88, v88
	v_exp_f32_e32 v73, v73
	v_exp_f32_e32 v89, v89
	v_exp_f32_e32 v74, v74
	v_exp_f32_e32 v90, v90
	v_exp_f32_e32 v75, v75
	v_exp_f32_e32 v91, v91
	v_exp_f32_e32 v76, v76
	v_exp_f32_e32 v92, v92
	v_exp_f32_e32 v77, v77
	v_exp_f32_e32 v93, v93
	v_exp_f32_e32 v78, v78
	v_exp_f32_e32 v94, v94
	v_exp_f32_e32 v79, v79
	v_exp_f32_e32 v95, v95
	v_exp_f32_e32 v80, v80
	v_exp_f32_e32 v96, v96
	v_exp_f32_e32 v81, v81
	v_exp_f32_e32 v97, v97
	v_add_u32_e32 v228, s19, v226
	v_add3_u32 v248, v228, v168, s33
	ds_read_b64 v[228:229], v248 offset:0
	ds_read_b64 v[230:231], v248 offset:16
	ds_read_b64 v[232:233], v248 offset:0x1100
	ds_read_b64 v[234:235], v248 offset:0x1110
	ds_read_b64 v[236:237], v248 offset:0x2200
	ds_read_b64 v[238:239], v248 offset:0x2210
	ds_read_b64 v[240:241], v248 offset:0x3300
	ds_read_b64 v[242:243], v248 offset:0x3310
	s_setprio 1
	s_waitcnt lgkmcnt(4)
	v_cvt_pk_bf16_f32 v244, v66, v67
	v_cvt_pk_bf16_f32 v245, v68, v69
	v_cvt_pk_bf16_f32 v246, v70, v71
	v_cvt_pk_bf16_f32 v247, v72, v73
	s_nop 1
	v_mfma_f32_32x32x16_bf16 v[50:65], v[228:231], v[244:247], v[50:65]
	ds_read_b64 v[228:229], v248 offset:32
	ds_read_b64 v[230:231], v248 offset:48
	v_mfma_f32_32x32x16_bf16 v[34:49], v[232:235], v[244:247], v[34:49]
	ds_read_b64 v[232:233], v248 offset:0x1120
	ds_read_b64 v[234:235], v248 offset:0x1130
	s_waitcnt lgkmcnt(4)
	v_mfma_f32_32x32x16_bf16 v[18:33], v[236:239], v[244:247], v[18:33]
	ds_read_b64 v[236:237], v248 offset:0x2220
	ds_read_b64 v[238:239], v248 offset:0x2230
	v_mfma_f32_32x32x16_bf16 v[2:17], v[240:243], v[244:247], v[2:17]
	ds_read_b64 v[240:241], v248 offset:0x3320
	ds_read_b64 v[242:243], v248 offset:0x3330
	s_waitcnt lgkmcnt(4)
	v_cvt_pk_bf16_f32 v244, v74, v75
	v_cvt_pk_bf16_f32 v245, v76, v77
	v_cvt_pk_bf16_f32 v246, v78, v79
	v_cvt_pk_bf16_f32 v247, v80, v81
	s_nop 1
	v_mfma_f32_32x32x16_bf16 v[50:65], v[228:231], v[244:247], v[50:65]
	ds_read_b64 v[228:229], v248 offset:64
	ds_read_b64 v[230:231], v248 offset:0x50
	v_mfma_f32_32x32x16_bf16 v[34:49], v[232:235], v[244:247], v[34:49]
	ds_read_b64 v[232:233], v248 offset:0x1140
	ds_read_b64 v[234:235], v248 offset:0x1150
	s_waitcnt lgkmcnt(4)
	v_mfma_f32_32x32x16_bf16 v[18:33], v[236:239], v[244:247], v[18:33]
	ds_read_b64 v[236:237], v248 offset:0x2240
	ds_read_b64 v[238:239], v248 offset:0x2250
	v_mfma_f32_32x32x16_bf16 v[2:17], v[240:243], v[244:247], v[2:17]
	ds_read_b64 v[240:241], v248 offset:0x3340
	ds_read_b64 v[242:243], v248 offset:0x3350
	s_waitcnt lgkmcnt(4)
	v_cvt_pk_bf16_f32 v244, v82, v83
	v_cvt_pk_bf16_f32 v245, v84, v85
	v_cvt_pk_bf16_f32 v246, v86, v87
	v_cvt_pk_bf16_f32 v247, v88, v89
	s_nop 1
	v_mfma_f32_32x32x16_bf16 v[50:65], v[228:231], v[244:247], v[50:65]
	ds_read_b64 v[228:229], v248 offset:0x60
	ds_read_b64 v[230:231], v248 offset:0x70
	v_mfma_f32_32x32x16_bf16 v[34:49], v[232:235], v[244:247], v[34:49]
	ds_read_b64 v[232:233], v248 offset:0x1160
	ds_read_b64 v[234:235], v248 offset:0x1170
	s_waitcnt lgkmcnt(4)
	v_mfma_f32_32x32x16_bf16 v[18:33], v[236:239], v[244:247], v[18:33]
	ds_read_b64 v[236:237], v248 offset:0x2260
	ds_read_b64 v[238:239], v248 offset:0x2270
	v_mfma_f32_32x32x16_bf16 v[2:17], v[240:243], v[244:247], v[2:17]
	ds_read_b64 v[240:241], v248 offset:0x3360
	ds_read_b64 v[242:243], v248 offset:0x3370
	s_waitcnt lgkmcnt(4)
	v_cvt_pk_bf16_f32 v244, v90, v91
	v_cvt_pk_bf16_f32 v245, v92, v93
	v_cvt_pk_bf16_f32 v246, v94, v95
	v_cvt_pk_bf16_f32 v247, v96, v97
	s_nop 1
	v_mfma_f32_32x32x16_bf16 v[50:65], v[228:231], v[244:247], v[50:65]
	v_mfma_f32_32x32x16_bf16 v[34:49], v[232:235], v[244:247], v[34:49]
	s_waitcnt lgkmcnt(0)
	v_mfma_f32_32x32x16_bf16 v[18:33], v[236:239], v[244:247], v[18:33]
	v_mfma_f32_32x32x16_bf16 v[2:17], v[240:243], v[244:247], v[2:17]
	s_andn2_b64 vcc, exec, s[10:11]
	s_cbranch_vccnz .LBB0_827
	s_bitcmp1_b32 s18, 0
	s_cselect_b32 s6, 0xa800, 0
	v_add3_u32 v228, s6, v167, v169
	v_add3_u32 v229, s6, v199, v217
	v_add3_u32 v230, s6, v220, v221
	s_waitcnt vmcnt(2)
	ds_write_b128 v228, v[146:149]
	s_waitcnt vmcnt(1)
	ds_write_b128 v229, v[154:157]
	s_waitcnt vmcnt(0)
	ds_write_b128 v230, v[162:165]

; DI unsigned pk2(float a, float b) { f32v2 f = {a, b}; bf16v2 r = __builtin_convertvector(f, bf16v2); return __builtin_bit_cast(unsigned, r); }
; DI float bflo(unsigned w) { return __uint_as_float(w << 16); }
; DI float bfhi(unsigned w) { return __uint_as_float(w & 0xffff0000u); }
; DI void store_gated(const Params& p, int R, int colbase, f32x16 (&o)[4], float mult, const float* wv, int h) {
; #pragma unroll
;   for (int d0 = 0; d0 < 4; ++d0)
; #pragma unroll
;     for (int g = 0; g < 4; ++g) {
;       const int dv = 32 * d0 + 8 * g + 4 * h;
;       const size_t off = (size_t)R * DM + colbase + dv;
;       const u32x2 gg = *(const u32x2*)(p.Gs + off);
;       float v0 = o[d0][4 * g] * mult, v1 = o[d0][4 * g + 1] * mult, v2 = o[d0][4 * g + 2] * mult, v3 = o[d0][4 * g + 3] * mult;
;       if (wv) { v0 *= wv[dv]; v1 *= wv[dv + 1]; v2 *= wv[dv + 2]; v3 *= wv[dv + 3]; }
;       u32x2 ov = {pk2(v0 * bflo(gg[0]), v1 * bfhi(gg[0])), pk2(v2 * bflo(gg[1]), v3 * bfhi(gg[1]))};
;       *(u32x2*)(p.H + off) = ov;
;       __builtin_amdgcn_sched_barrier(0);
;     }
; }
;     ...
;       const int j = it - N_DIFF, hd = j / 65, qb = j % 65, q0 = qb * 256, nt = qb == 0 ? 4 : NR / 64;
;       attn_core<192, 0, false>(p.Qmla + ((size_t)hd * NR + q0) * 192, p.Kmla + (size_t)hd * NR * 192, p.VtMla + (size_t)hd * 128 * NR, nt, 0, 0, 0, 0, 0, biasL, lds, o, l, tid);
;       store_gated(p, q0 + wid * 32 + r32, hd * 128, o, 1.f / l, nullptr, h);
.LBB0_831:
	s_setprio 0
	s_and_b32 s0, 0xffff, s16
	v_lshl_add_u32 v0, v197, 5, s0
	v_or_b32_e32 v66, v0, v193
	v_ashrrev_i32_e32 v67, 31, v66
	s_lshl_b32 s12, s12, 7
	v_lshlrev_b64 v[66:67], 11, v[66:67]
	v_lshl_add_u64 v[66:67], v[66:67], 0, s[12:13]
	v_lshl_or_b32 v66, v195, 2, v66
	v_readlane_b32 s8, v252, 2
	v_lshlrev_b64 v[68:69], 1, v[66:67]
	v_readlane_b32 s10, v252, 4
	v_readlane_b32 s11, v252, 5
	v_and_b32_e32 v72, 64, v189
	v_xor_b32_e32 v0, 32, v189
	v_lshl_add_u64 v[66:67], s[10:11], 0, v[68:69]
	global_load_dwordx2 v[70:71], v[66:67], off
	v_add_u32_e32 v72, 64, v72
	v_cmp_lt_i32_e32 vcc, v0, v72
	v_readlane_b32 s9, v252, 3
	s_nop 0
	v_cndmask_b32_e32 v0, v189, v0, vcc
	v_lshlrev_b32_e32 v0, 2, v0
	ds_bpermute_b32 v0, v0, v222
	s_waitcnt lgkmcnt(0)
	v_add_f32_e32 v0, v222, v0
	v_div_scale_f32 v72, s[0:1], v0, v0, 1.0
	v_rcp_f32_e32 v73, v72
	v_div_scale_f32 v74, vcc, 1.0, v0, 1.0
	v_fma_f32 v75, -v72, v73, 1.0
	v_fmac_f32_e32 v73, v75, v73
	v_mul_f32_e32 v75, v74, v73
	v_fma_f32 v76, -v72, v75, v74
	v_fmac_f32_e32 v75, v76, v73
	v_fma_f32 v72, -v72, v75, v74
	v_div_fmas_f32 v72, v72, v73, v75
	v_div_fixup_f32 v0, v72, v0, 1.0
	v_pk_mul_f32 v[50:51], v[50:51], v[0:1] op_sel_hi:[1,0]
	v_pk_mul_f32 v[52:53], v[52:53], v[0:1] op_sel_hi:[1,0]
	s_waitcnt vmcnt(0)
	v_lshlrev_b32_e32 v72, 16, v70
	v_and_b32_e32 v73, 0xffff0000, v70
	v_lshlrev_b32_e32 v70, 16, v71
	v_and_b32_e32 v71, 0xffff0000, v71
	v_pk_mul_f32 v[50:51], v[50:51], v[72:73]
	v_pk_mul_f32 v[52:53], v[52:53], v[70:71]
	v_cvt_pk_bf16_f32 v70, v50, v51
	v_cvt_pk_bf16_f32 v71, v52, v53
	v_lshl_add_u64 v[50:51], s[74:75], 0, v[68:69]
	global_store_dwordx2 v[50:51], v[70:71], off
	global_load_dwordx2 v[52:53], v[66:67], off offset:16
	v_pk_mul_f32 v[54:55], v[54:55], v[0:1] op_sel_hi:[1,0]
	s_waitcnt vmcnt(0)
	v_lshlrev_b32_e32 v68, 16, v52
	v_and_b32_e32 v69, 0xffff0000, v52
	v_pk_mul_f32 v[54:55], v[54:55], v[68:69]
	s_nop 0
	v_cvt_pk_bf16_f32 v52, v54, v55
	v_pk_mul_f32 v[54:55], v[56:57], v[0:1] op_sel_hi:[1,0]
	v_lshlrev_b32_e32 v56, 16, v53
	v_and_b32_e32 v57, 0xffff0000, v53
	v_pk_mul_f32 v[54:55], v[54:55], v[56:57]
	s_nop 0
	v_cvt_pk_bf16_f32 v53, v54, v55
	global_store_dwordx2 v[50:51], v[52:53], off offset:16
	global_load_dwordx2 v[52:53], v[66:67], off offset:32
	v_pk_mul_f32 v[54:55], v[58:59], v[0:1] op_sel_hi:[1,0]
	s_waitcnt vmcnt(0)
	v_lshlrev_b32_e32 v56, 16, v52
	v_and_b32_e32 v57, 0xffff0000, v52
	v_pk_mul_f32 v[54:55], v[54:55], v[56:57]
	v_lshlrev_b32_e32 v56, 16, v53
	v_cvt_pk_bf16_f32 v52, v54, v55
	v_pk_mul_f32 v[54:55], v[60:61], v[0:1] op_sel_hi:[1,0]
	v_and_b32_e32 v57, 0xffff0000, v53
	v_pk_mul_f32 v[54:55], v[54:55], v[56:57]
	s_nop 0
	v_cvt_pk_bf16_f32 v53, v54, v55
	global_store_dwordx2 v[50:51], v[52:53], off offset:32
	global_load_dwordx2 v[52:53], v[66:67], off offset:48
	v_pk_mul_f32 v[54:55], v[62:63], v[0:1] op_sel_hi:[1,0]
	v_pk_mul_f32 v[56:57], v[64:65], v[0:1] op_sel_hi:[1,0]
	s_waitcnt vmcnt(0)
	v_lshlrev_b32_e32 v58, 16, v52
	v_and_b32_e32 v59, 0xffff0000, v52
	v_lshlrev_b32_e32 v52, 16, v53
	v_and_b32_e32 v53, 0xffff0000, v53
	v_pk_mul_f32 v[54:55], v[54:55], v[58:59]
	v_pk_mul_f32 v[52:53], v[56:57], v[52:53]
	v_cvt_pk_bf16_f32 v54, v54, v55
	v_cvt_pk_bf16_f32 v55, v52, v53
	global_store_dwordx2 v[50:51], v[54:55], off offset:48
	global_load_dwordx2 v[52:53], v[66:67], off offset:64
	v_pk_mul_f32 v[34:35], v[34:35], v[0:1] op_sel_hi:[1,0]
	v_pk_mul_f32 v[36:37], v[36:37], v[0:1] op_sel_hi:[1,0]
	s_waitcnt vmcnt(0)
	v_lshlrev_b32_e32 v54, 16, v52
	v_and_b32_e32 v55, 0xffff0000, v52
	v_lshlrev_b32_e32 v52, 16, v53
	v_and_b32_e32 v53, 0xffff0000, v53
	v_pk_mul_f32 v[34:35], v[34:35], v[54:55]
	v_pk_mul_f32 v[36:37], v[36:37], v[52:53]
	v_cvt_pk_bf16_f32 v34, v34, v35
	v_cvt_pk_bf16_f32 v35, v36, v37
	global_store_dwordx2 v[50:51], v[34:35], off offset:64
	global_load_dwordx2 v[34:35], v[66:67], off offset:80
	v_pk_mul_f32 v[36:37], v[38:39], v[0:1] op_sel_hi:[1,0]
	s_waitcnt vmcnt(0)
	v_lshlrev_b32_e32 v38, 16, v34
	v_and_b32_e32 v39, 0xffff0000, v34
	v_pk_mul_f32 v[36:37], v[36:37], v[38:39]
	v_lshlrev_b32_e32 v38, 16, v35
	v_cvt_pk_bf16_f32 v34, v36, v37
	v_pk_mul_f32 v[36:37], v[40:41], v[0:1] op_sel_hi:[1,0]
	v_and_b32_e32 v39, 0xffff0000, v35
	v_pk_mul_f32 v[36:37], v[36:37], v[38:39]
	s_nop 0
	v_cvt_pk_bf16_f32 v35, v36, v37
	global_store_dwordx2 v[50:51], v[34:35], off offset:80
	global_load_dwordx2 v[34:35], v[66:67], off offset:96
	v_pk_mul_f32 v[36:37], v[42:43], v[0:1] op_sel_hi:[1,0]
	s_waitcnt vmcnt(0)
	v_lshlrev_b32_e32 v38, 16, v34
	v_and_b32_e32 v39, 0xffff0000, v34
	v_pk_mul_f32 v[36:37], v[36:37], v[38:39]
	v_lshlrev_b32_e32 v38, 16, v35
	v_cvt_pk_bf16_f32 v34, v36, v37
	v_pk_mul_f32 v[36:37], v[44:45], v[0:1] op_sel_hi:[1,0]
	v_and_b32_e32 v39, 0xffff0000, v35
	v_pk_mul_f32 v[36:37], v[36:37], v[38:39]
	s_nop 0
	v_cvt_pk_bf16_f32 v35, v36, v37
	global_store_dwordx2 v[50:51], v[34:35], off offset:96
	global_load_dwordx2 v[34:35], v[66:67], off offset:112
	v_pk_mul_f32 v[36:37], v[46:47], v[0:1] op_sel_hi:[1,0]
	v_pk_mul_f32 v[38:39], v[48:49], v[0:1] op_sel_hi:[1,0]
	s_waitcnt vmcnt(0)
; DI unsigned pk2(float a, float b) { f32v2 f = {a, b}; bf16v2 r = __builtin_convertvector(f, bf16v2); return __builtin_bit_cast(unsigned, r); }
; DI float bflo(unsigned w) { return __uint_as_float(w << 16); }
; DI float bfhi(unsigned w) { return __uint_as_float(w & 0xffff0000u); }
; DI void store_gated(const Params& p, int R, int colbase, f32x16 (&o)[4], float mult, const float* wv, int h) {
; #pragma unroll
;   for (int d0 = 0; d0 < 4; ++d0)
; #pragma unroll
;     for (int g = 0; g < 4; ++g) {
;       const int dv = 32 * d0 + 8 * g + 4 * h;
;       const size_t off = (size_t)R * DM + colbase + dv;
;       const u32x2 gg = *(const u32x2*)(p.Gs + off);
;       float v0 = o[d0][4 * g] * mult, v1 = o[d0][4 * g + 1] * mult, v2 = o[d0][4 * g + 2] * mult, v3 = o[d0][4 * g + 3] * mult;
;       if (wv) { v0 *= wv[dv]; v1 *= wv[dv + 1]; v2 *= wv[dv + 2]; v3 *= wv[dv + 3]; }
;       u32x2 ov = {pk2(v0 * bflo(gg[0]), v1 * bfhi(gg[0])), pk2(v2 * bflo(gg[1]), v3 * bfhi(gg[1]))};
;       *(u32x2*)(p.H + off) = ov;
;       __builtin_amdgcn_sched_barrier(0);
;     }
; }
	v_lshlrev_b32_e32 v40, 16, v34
	v_and_b32_e32 v41, 0xffff0000, v34
	v_lshlrev_b32_e32 v34, 16, v35
	v_and_b32_e32 v35, 0xffff0000, v35
	v_pk_mul_f32 v[36:37], v[36:37], v[40:41]
	v_pk_mul_f32 v[34:35], v[38:39], v[34:35]
	v_cvt_pk_bf16_f32 v36, v36, v37
	v_cvt_pk_bf16_f32 v37, v34, v35
	global_store_dwordx2 v[50:51], v[36:37], off offset:112
	global_load_dwordx2 v[34:35], v[66:67], off offset:128
	v_pk_mul_f32 v[18:19], v[18:19], v[0:1] op_sel_hi:[1,0]
	v_pk_mul_f32 v[20:21], v[20:21], v[0:1] op_sel_hi:[1,0]
	s_waitcnt vmcnt(0)
	v_lshlrev_b32_e32 v36, 16, v34
	v_and_b32_e32 v37, 0xffff0000, v34
	v_lshlrev_b32_e32 v34, 16, v35
	v_and_b32_e32 v35, 0xffff0000, v35
	v_pk_mul_f32 v[18:19], v[18:19], v[36:37]
	v_pk_mul_f32 v[20:21], v[20:21], v[34:35]
	v_cvt_pk_bf16_f32 v18, v18, v19
	v_cvt_pk_bf16_f32 v19, v20, v21
	global_store_dwordx2 v[50:51], v[18:19], off offset:128
	global_load_dwordx2 v[18:19], v[66:67], off offset:144
	v_pk_mul_f32 v[20:21], v[22:23], v[0:1] op_sel_hi:[1,0]
	s_waitcnt vmcnt(0)
	v_lshlrev_b32_e32 v22, 16, v18
	v_and_b32_e32 v23, 0xffff0000, v18
	v_pk_mul_f32 v[20:21], v[20:21], v[22:23]
	v_lshlrev_b32_e32 v22, 16, v19
	v_cvt_pk_bf16_f32 v18, v20, v21
	v_pk_mul_f32 v[20:21], v[24:25], v[0:1] op_sel_hi:[1,0]
	v_and_b32_e32 v23, 0xffff0000, v19
	v_pk_mul_f32 v[20:21], v[20:21], v[22:23]
	s_nop 0
	v_cvt_pk_bf16_f32 v19, v20, v21
	global_store_dwordx2 v[50:51], v[18:19], off offset:144
	global_load_dwordx2 v[18:19], v[66:67], off offset:160
	v_pk_mul_f32 v[20:21], v[26:27], v[0:1] op_sel_hi:[1,0]
	s_waitcnt vmcnt(0)
	v_lshlrev_b32_e32 v22, 16, v18
	v_and_b32_e32 v23, 0xffff0000, v18
	v_pk_mul_f32 v[20:21], v[20:21], v[22:23]
	v_lshlrev_b32_e32 v22, 16, v19
	v_cvt_pk_bf16_f32 v18, v20, v21
	v_pk_mul_f32 v[20:21], v[28:29], v[0:1] op_sel_hi:[1,0]
	v_and_b32_e32 v23, 0xffff0000, v19
	v_pk_mul_f32 v[20:21], v[20:21], v[22:23]
	s_nop 0
	v_cvt_pk_bf16_f32 v19, v20, v21
	global_store_dwordx2 v[50:51], v[18:19], off offset:160
	global_load_dwordx2 v[18:19], v[66:67], off offset:176
	v_pk_mul_f32 v[20:21], v[30:31], v[0:1] op_sel_hi:[1,0]
	v_pk_mul_f32 v[22:23], v[32:33], v[0:1] op_sel_hi:[1,0]
	s_waitcnt vmcnt(0)
	v_lshlrev_b32_e32 v24, 16, v18
	v_and_b32_e32 v25, 0xffff0000, v18
	v_lshlrev_b32_e32 v18, 16, v19
	v_and_b32_e32 v19, 0xffff0000, v19
	v_pk_mul_f32 v[20:21], v[20:21], v[24:25]
	v_pk_mul_f32 v[18:19], v[22:23], v[18:19]
	v_cvt_pk_bf16_f32 v20, v20, v21
	v_cvt_pk_bf16_f32 v21, v18, v19
	global_store_dwordx2 v[50:51], v[20:21], off offset:176
	global_load_dwordx2 v[18:19], v[66:67], off offset:192
	v_pk_mul_f32 v[2:3], v[2:3], v[0:1] op_sel_hi:[1,0]
	v_pk_mul_f32 v[4:5], v[4:5], v[0:1] op_sel_hi:[1,0]
	s_waitcnt vmcnt(0)
	v_lshlrev_b32_e32 v20, 16, v18
	v_and_b32_e32 v21, 0xffff0000, v18
	v_lshlrev_b32_e32 v18, 16, v19
	v_and_b32_e32 v19, 0xffff0000, v19
	v_pk_mul_f32 v[2:3], v[2:3], v[20:21]
	v_pk_mul_f32 v[4:5], v[4:5], v[18:19]
	v_cvt_pk_bf16_f32 v2, v2, v3
	v_cvt_pk_bf16_f32 v3, v4, v5
	global_store_dwordx2 v[50:51], v[2:3], off offset:192
	global_load_dwordx2 v[2:3], v[66:67], off offset:208
	v_pk_mul_f32 v[4:5], v[6:7], v[0:1] op_sel_hi:[1,0]
	s_waitcnt vmcnt(0)
	v_lshlrev_b32_e32 v6, 16, v2
	v_and_b32_e32 v7, 0xffff0000, v2
	v_pk_mul_f32 v[4:5], v[4:5], v[6:7]
	v_lshlrev_b32_e32 v6, 16, v3
	v_cvt_pk_bf16_f32 v2, v4, v5
	v_pk_mul_f32 v[4:5], v[8:9], v[0:1] op_sel_hi:[1,0]
	v_and_b32_e32 v7, 0xffff0000, v3
	v_pk_mul_f32 v[4:5], v[4:5], v[6:7]
	s_nop 0
	v_cvt_pk_bf16_f32 v3, v4, v5
	global_store_dwordx2 v[50:51], v[2:3], off offset:208
	global_load_dwordx2 v[2:3], v[66:67], off offset:224
	v_pk_mul_f32 v[4:5], v[10:11], v[0:1] op_sel_hi:[1,0]
	s_waitcnt vmcnt(0)
	v_lshlrev_b32_e32 v6, 16, v2
	v_and_b32_e32 v7, 0xffff0000, v2
	v_pk_mul_f32 v[4:5], v[4:5], v[6:7]
	v_lshlrev_b32_e32 v6, 16, v3
	v_cvt_pk_bf16_f32 v2, v4, v5
	v_pk_mul_f32 v[4:5], v[12:13], v[0:1] op_sel_hi:[1,0]
	v_and_b32_e32 v7, 0xffff0000, v3
	v_pk_mul_f32 v[4:5], v[4:5], v[6:7]
	s_nop 0
	v_cvt_pk_bf16_f32 v3, v4, v5
	global_store_dwordx2 v[50:51], v[2:3], off offset:224
	global_load_dwordx2 v[2:3], v[66:67], off offset:240
	v_pk_mul_f32 v[4:5], v[14:15], v[0:1] op_sel_hi:[1,0]
	v_pk_mul_f32 v[6:7], v[16:17], v[0:1] op_sel_hi:[1,0]
	s_waitcnt vmcnt(0)
	v_lshlrev_b32_e32 v8, 16, v2
	v_and_b32_e32 v9, 0xffff0000, v2
	v_lshlrev_b32_e32 v2, 16, v3
	v_and_b32_e32 v3, 0xffff0000, v3
	v_pk_mul_f32 v[4:5], v[4:5], v[8:9]
	v_pk_mul_f32 v[2:3], v[6:7], v[2:3]
	v_cvt_pk_bf16_f32 v4, v4, v5
	v_cvt_pk_bf16_f32 v5, v2, v3
	global_store_dwordx2 v[50:51], v[4:5], off offset:240

; #define SBAR() __builtin_amdgcn_sched_barrier(0)
; template <int DQK, int MODE, bool PIPE>
; DI void attn_core(const u16* __restrict__ Qg, const u16* __restrict__ Kg, const u16* __restrict__ Vtg, int ntiles,
;                   int kr_lo, int rs, int r_q, int c_q, int cs, const float* biasL, char* lds, f32x16 (&o)[4], float& l_out, int tid) {
;     ...
;     for (int i = 0; i < 16; ++i) { p0[i] = __builtin_amdgcn_exp2f(p0[i]); p1[i] = __builtin_amdgcn_exp2f(p1[i]); ps += p0[i] + p1[i]; }
;     l += ps;
;     const char* vb = lds + (t & 1) * A_BUF + A_VOFF + r32 * 136 + h * 8;
;     {
;       bf16x8 pfc;
;       constexpr int R = PV_RING;
;       const unsigned vaddr = (unsigned)(size_t)vb;
;       s16x4 vlo[R], vhi[R];
;       SBAR();
;       vlo[0] = lds_rd64<0>(vaddr); vhi[0] = lds_rd64<16>(vaddr);
;       vlo[1] = lds_rd64<32 * 136>(vaddr); vhi[1] = lds_rd64<32 * 136 + 16>(vaddr);
;       if (R > 2) { vlo[2 % R] = lds_rd64<64 * 136>(vaddr); vhi[2 % R] = lds_rd64<64 * 136 + 16>(vaddr); }
;       if (R > 3) { vlo[3 % R] = lds_rd64<96 * 136>(vaddr); vhi[3 % R] = lds_rd64<96 * 136 + 16>(vaddr); }
;       SBAR();
;       __builtin_amdgcn_s_setprio(1);
;       PvStep<0, 16, R>::run(vaddr, vlo, vhi, p0, p1, pfc, o);
;       __builtin_amdgcn_s_setprio(0);
;     ...
;       if (t + 2 < ntiles) swriteK(t & 1);
;       if (t + 3 < ntiles) gloadK(t + 3);
;     } else {
;       if (is_active(t)) { qk(t, c0, c1); sm_pv(t, c0, c1); }
;       if (t + 1 < ntiles) swriteK((t + 1) & 1);
;       if (t + 2 < ntiles) gloadK(t + 2);
.LBB0_844:
	v_exp_f32_e32 v82, v82
	v_exp_f32_e32 v98, v98
	v_exp_f32_e32 v83, v83
	v_exp_f32_e32 v99, v99
	v_exp_f32_e32 v84, v84
	v_exp_f32_e32 v100, v100
	v_exp_f32_e32 v85, v85
	v_exp_f32_e32 v101, v101
	v_exp_f32_e32 v86, v86
	v_exp_f32_e32 v102, v102
	v_exp_f32_e32 v87, v87
	v_exp_f32_e32 v103, v103
	v_exp_f32_e32 v88, v88
	v_exp_f32_e32 v104, v104
	v_exp_f32_e32 v89, v89
	v_exp_f32_e32 v105, v105
	v_exp_f32_e32 v90, v90
	v_exp_f32_e32 v106, v106
	v_exp_f32_e32 v91, v91
	v_exp_f32_e32 v107, v107
	v_exp_f32_e32 v92, v92
	v_exp_f32_e32 v108, v108
	v_exp_f32_e32 v93, v93
	v_exp_f32_e32 v109, v109
	v_exp_f32_e32 v94, v94
	v_exp_f32_e32 v110, v110
	v_exp_f32_e32 v95, v95
	v_exp_f32_e32 v111, v111
	v_exp_f32_e32 v96, v96
	v_exp_f32_e32 v112, v112
	v_exp_f32_e32 v97, v97
	v_exp_f32_e32 v113, v113
	v_add_u32_e32 v177, s15, v168
	v_add3_u32 v177, v177, v166, s33
	ds_read_b64 v[216:217], v177 offset:0
	ds_read_b64 v[218:219], v177 offset:16
	ds_read_b64 v[220:221], v177 offset:0x1100
	ds_read_b64 v[222:223], v177 offset:0x1110
	ds_read_b64 v[224:225], v177 offset:0x2200
	ds_read_b64 v[226:227], v177 offset:0x2210
	ds_read_b64 v[228:229], v177 offset:0x3300
	ds_read_b64 v[230:231], v177 offset:0x3310
	s_setprio 1
	s_waitcnt lgkmcnt(4)
	v_cvt_pk_bf16_f32 v232, v82, v83
	v_cvt_pk_bf16_f32 v233, v84, v85
	v_cvt_pk_bf16_f32 v234, v86, v87
	v_cvt_pk_bf16_f32 v235, v88, v89
	s_nop 1
	v_mfma_f32_32x32x16_bf16 v[66:81], v[216:219], v[232:235], v[66:81]
	ds_read_b64 v[216:217], v177 offset:32
	ds_read_b64 v[218:219], v177 offset:48
	v_mfma_f32_32x32x16_bf16 v[50:65], v[220:223], v[232:235], v[50:65]
	ds_read_b64 v[220:221], v177 offset:0x1120
	ds_read_b64 v[222:223], v177 offset:0x1130
	s_waitcnt lgkmcnt(4)
	v_mfma_f32_32x32x16_bf16 v[34:49], v[224:227], v[232:235], v[34:49]
	ds_read_b64 v[224:225], v177 offset:0x2220
	ds_read_b64 v[226:227], v177 offset:0x2230
	v_mfma_f32_32x32x16_bf16 v[2:17], v[228:231], v[232:235], v[2:17]
	ds_read_b64 v[228:229], v177 offset:0x3320
	ds_read_b64 v[230:231], v177 offset:0x3330
	s_waitcnt lgkmcnt(4)
	v_cvt_pk_bf16_f32 v232, v90, v91
	v_cvt_pk_bf16_f32 v233, v92, v93
	v_cvt_pk_bf16_f32 v234, v94, v95
	v_cvt_pk_bf16_f32 v235, v96, v97
	s_nop 1
	v_mfma_f32_32x32x16_bf16 v[66:81], v[216:219], v[232:235], v[66:81]
	ds_read_b64 v[216:217], v177 offset:64
	ds_read_b64 v[218:219], v177 offset:0x50
	v_mfma_f32_32x32x16_bf16 v[50:65], v[220:223], v[232:235], v[50:65]
	ds_read_b64 v[220:221], v177 offset:0x1140
	ds_read_b64 v[222:223], v177 offset:0x1150
	s_waitcnt lgkmcnt(4)
	v_mfma_f32_32x32x16_bf16 v[34:49], v[224:227], v[232:235], v[34:49]
	ds_read_b64 v[224:225], v177 offset:0x2240
	ds_read_b64 v[226:227], v177 offset:0x2250
	v_mfma_f32_32x32x16_bf16 v[2:17], v[228:231], v[232:235], v[2:17]
	ds_read_b64 v[228:229], v177 offset:0x3340
	ds_read_b64 v[230:231], v177 offset:0x3350
	s_waitcnt lgkmcnt(4)
	v_cvt_pk_bf16_f32 v232, v98, v99
	v_cvt_pk_bf16_f32 v233, v100, v101
	v_cvt_pk_bf16_f32 v234, v102, v103
	v_cvt_pk_bf16_f32 v235, v104, v105
	s_nop 1
	v_mfma_f32_32x32x16_bf16 v[66:81], v[216:219], v[232:235], v[66:81]
	ds_read_b64 v[216:217], v177 offset:0x60
	ds_read_b64 v[218:219], v177 offset:0x70
	v_mfma_f32_32x32x16_bf16 v[50:65], v[220:223], v[232:235], v[50:65]
	ds_read_b64 v[220:221], v177 offset:0x1160
	ds_read_b64 v[222:223], v177 offset:0x1170
	s_waitcnt lgkmcnt(4)
	v_mfma_f32_32x32x16_bf16 v[34:49], v[224:227], v[232:235], v[34:49]
	ds_read_b64 v[224:225], v177 offset:0x2260
	ds_read_b64 v[226:227], v177 offset:0x2270
	v_mfma_f32_32x32x16_bf16 v[2:17], v[228:231], v[232:235], v[2:17]
	ds_read_b64 v[228:229], v177 offset:0x3360
	ds_read_b64 v[230:231], v177 offset:0x3370
	s_waitcnt lgkmcnt(4)
	v_cvt_pk_bf16_f32 v232, v106, v107
	v_cvt_pk_bf16_f32 v233, v108, v109
	v_cvt_pk_bf16_f32 v234, v110, v111
	v_cvt_pk_bf16_f32 v235, v112, v113
	s_nop 1
	v_mfma_f32_32x32x16_bf16 v[66:81], v[216:219], v[232:235], v[66:81]
	v_mfma_f32_32x32x16_bf16 v[50:65], v[220:223], v[232:235], v[50:65]
	s_waitcnt lgkmcnt(0)
	v_mfma_f32_32x32x16_bf16 v[34:49], v[224:227], v[232:235], v[34:49]
	v_mfma_f32_32x32x16_bf16 v[2:17], v[228:231], v[232:235], v[2:17]
	s_andn2_b64 vcc, exec, s[0:1]
	s_cbranch_vccnz .LBB0_846
	s_bitcmp1_b32 s14, 0
	s_cselect_b32 s0, 0xa800, 0
	v_add_u32_e32 v177, s0, v143
	s_waitcnt vmcnt(0)
	ds_write_b128 v177, v[138:141]

; template <int DQK, int MODE, bool PIPE>
; DI void attn_core(const u16* __restrict__ Qg, const u16* __restrict__ Kg, const u16* __restrict__ Vtg, int ntiles,
;                   int kr_lo, int rs, int r_q, int c_q, int cs, const float* biasL, char* lds, f32x16 (&o)[4], float& l_out, int tid) {
;     ...
;     const u16* qrow = Qg + (size_t)(wid * 32 + r32) * DQK + h * 8;
; #pragma unroll
;     for (int ks = 0; ks < NKS; ++ks) qf[ks] = *(const bf16x8*)(qrow + ks * 16);
;   }
; #pragma unroll
;   for (int d = 0; d < 4; ++d)
; #pragma unroll
;     for (int i = 0; i < 16; ++i) o[d][i] = 0.f;
;   float m = 0.f, l = 0.f;
;   constexpr bool NEGM = (MODE == 0 && DQK == 64);
;   f32x16 negm;
; #pragma unroll
;   for (int i = 0; i < 16; ++i) negm[i] = 0.f;
;   u32x4 rk[KPT], rv[2];
;   auto keystart = [&](int t) -> int { if (MODE == 1 && t >= 4) return NCTX + 64 * (kr_lo + t - 4); return 64 * t; };
;   auto gloadK = [&](int t) {
;     const u16* kp = Kg + (size_t)keystart(t) * DQK;
; #pragma unroll
;     for (int j = 0; j < KPT; ++j) rk[j] = *(const u32x4*)(kp + (size_t)(tid + NT_ * j) * 8);
;   };
;   auto gloadV = [&](int t) {
;     const int key0 = keystart(t);
; #pragma unroll
;     for (int j = 0; j < 2; ++j) { const int q = tid + NT_ * j; rv[j] = *(const u32x4*)(Vtg + (size_t)(q >> 3) * NR + key0 + (q & 7) * 8); }
;   };
;     ...
;       float* d1 = p.D1 + ((size_t)blockIdx.x * 256 + wid * 32 + r32) * 128 + 4 * h;
;       { const float inv = 1.f / l;
; #pragma unroll
;         for (int d = 0; d < 4; ++d)
; #pragma unroll
;           for (int g = 0; g < 4; ++g)
;             *(float4*)(d1 + 32 * d + 8 * g) = make_float4(o[d][4 * g] * inv, o[d][4 * g + 1] * inv, o[d][4 * g + 2] * inv, o[d][4 * g + 3] * inv); }
;       attn_core<64, 0, false>(p.Qd + ((size_t)(hd * 2 + 1) * NR + q0) * 64, p.Kd + (size_t)(hd * 2 + 1) * NR * 64, Vt, nt, 0, 0, 0, 0, 0, biasL, lds, o, l, tid);
.LBB0_850:
	s_setprio 0
	v_and_b32_e32 v19, 64, v189
	v_xor_b32_e32 v18, 32, v189
	v_add_u32_e32 v19, 64, v19
	v_cmp_lt_i32_e32 vcc, v18, v19
	v_lshlrev_b32_e32 v144, 5, v197
	v_readlane_b32 s0, v254, 1
	v_cndmask_b32_e32 v18, v189, v18, vcc
	v_lshlrev_b32_e32 v162, 2, v18
	ds_bpermute_b32 v18, v162, v176
	v_ashrrev_i32_e32 v145, 31, v144
	v_readlane_b32 s1, v254, 2
	s_or_b32 s6, s12, 1
	v_readlane_b32 s16, v252, 6
	s_waitcnt lgkmcnt(0)
	v_add_f32_e32 v20, v176, v18
	v_lshl_add_u64 v[18:19], s[0:1], 0, v[144:145]
	v_div_scale_f32 v21, s[0:1], v20, v20, 1.0
	v_rcp_f32_e32 v22, v21
	v_or_b32_e32 v18, v18, v193
	v_readlane_b32 s0, v252, 0
	v_lshlrev_b64 v[18:19], 9, v[18:19]
	v_readlane_b32 s1, v252, 1
	v_readlane_b32 s18, v252, 8
	v_readlane_b32 s19, v252, 9
	v_lshl_add_u64 v[18:19], s[0:1], 0, v[18:19]
	v_lshl_add_u64 v[150:151], v[18:19], 0, v[0:1]
	v_fma_f32 v18, -v21, v22, 1.0
	v_fmac_f32_e32 v22, v18, v22
	v_div_scale_f32 v18, vcc, 1.0, v20, 1.0
	v_mul_f32_e32 v19, v18, v22
	v_fma_f32 v23, -v21, v19, v18
	v_fmac_f32_e32 v19, v23, v22
	v_fma_f32 v18, -v21, v19, v18
	v_div_fmas_f32 v18, v18, v22, v19
	v_div_fixup_f32 v22, v18, v20, 1.0
	v_pk_mul_f32 v[18:19], v[66:67], v[22:23] op_sel_hi:[1,0]
	v_pk_mul_f32 v[20:21], v[68:69], v[22:23] op_sel_hi:[1,0]
	global_store_dwordx4 v[150:151], v[18:21], off
	s_mul_i32 s0, s6, 0x4100
	s_mul_hi_i32 s1, s6, 0x4100
	v_pk_mul_f32 v[18:19], v[70:71], v[22:23] op_sel_hi:[1,0]
	v_pk_mul_f32 v[20:21], v[72:73], v[22:23] op_sel_hi:[1,0]
	global_store_dwordx4 v[150:151], v[18:21], off offset:32
	s_add_u32 s0, s0, s9
	s_addc_u32 s1, s1, s11
	v_pk_mul_f32 v[18:19], v[74:75], v[22:23] op_sel_hi:[1,0]
	v_pk_mul_f32 v[20:21], v[76:77], v[22:23] op_sel_hi:[1,0]
	global_store_dwordx4 v[150:151], v[18:21], off offset:64
	s_lshl_b64 s[0:1], s[0:1], 7
	v_pk_mul_f32 v[2:3], v[2:3], v[22:23] op_sel_hi:[1,0]
	v_pk_mul_f32 v[18:19], v[78:79], v[22:23] op_sel_hi:[1,0]
	v_pk_mul_f32 v[20:21], v[80:81], v[22:23] op_sel_hi:[1,0]
	global_store_dwordx4 v[150:151], v[18:21], off offset:96
	v_pk_mul_f32 v[4:5], v[4:5], v[22:23] op_sel_hi:[1,0]
	s_add_u32 s0, s18, s0
	v_pk_mul_f32 v[18:19], v[50:51], v[22:23] op_sel_hi:[1,0]
	v_pk_mul_f32 v[20:21], v[52:53], v[22:23] op_sel_hi:[1,0]
	global_store_dwordx4 v[150:151], v[18:21], off offset:128
	global_store_dwordx4 v[150:151], v[2:5], off offset:384
	v_readlane_b32 s20, v252, 10
	v_pk_mul_f32 v[18:19], v[54:55], v[22:23] op_sel_hi:[1,0]
	v_pk_mul_f32 v[20:21], v[56:57], v[22:23] op_sel_hi:[1,0]
	global_store_dwordx4 v[150:151], v[18:21], off offset:160
	v_pk_mul_f32 v[2:3], v[6:7], v[22:23] op_sel_hi:[1,0]
	v_pk_mul_f32 v[4:5], v[8:9], v[22:23] op_sel_hi:[1,0]
	v_pk_mul_f32 v[18:19], v[58:59], v[22:23] op_sel_hi:[1,0]
	v_pk_mul_f32 v[20:21], v[60:61], v[22:23] op_sel_hi:[1,0]
	global_store_dwordx4 v[150:151], v[18:21], off offset:192
	s_addc_u32 s1, s19, s1
	s_mul_hi_i32 s7, s6, 0x208000
	v_pk_mul_f32 v[18:19], v[62:63], v[22:23] op_sel_hi:[1,0]
	v_pk_mul_f32 v[20:21], v[64:65], v[22:23] op_sel_hi:[1,0]
	global_store_dwordx4 v[150:151], v[18:21], off offset:224
	s_mul_i32 s6, s6, 0x208000
	global_store_dwordx4 v[150:151], v[2:5], off offset:416
	v_pk_mul_f32 v[18:19], v[34:35], v[22:23] op_sel_hi:[1,0]
	v_pk_mul_f32 v[20:21], v[36:37], v[22:23] op_sel_hi:[1,0]
	global_store_dwordx4 v[150:151], v[18:21], off offset:256
	v_pk_mul_f32 v[2:3], v[10:11], v[22:23] op_sel_hi:[1,0]
	v_pk_mul_f32 v[4:5], v[12:13], v[22:23] op_sel_hi:[1,0]
	v_pk_mul_f32 v[18:19], v[38:39], v[22:23] op_sel_hi:[1,0]
	v_pk_mul_f32 v[20:21], v[40:41], v[22:23] op_sel_hi:[1,0]
	global_store_dwordx4 v[150:151], v[18:21], off offset:288
	v_readlane_b32 s21, v252, 11
	s_add_u32 s6, s20, s6
	v_pk_mul_f32 v[18:19], v[42:43], v[22:23] op_sel_hi:[1,0]
	v_pk_mul_f32 v[20:21], v[44:45], v[22:23] op_sel_hi:[1,0]
	global_store_dwordx4 v[150:151], v[18:21], off offset:320
	global_store_dwordx4 v[150:151], v[2:5], off offset:448
	s_addc_u32 s7, s21, s7
	v_pk_mul_f32 v[18:19], v[46:47], v[22:23] op_sel_hi:[1,0]
	v_pk_mul_f32 v[20:21], v[48:49], v[22:23] op_sel_hi:[1,0]
	v_pk_mul_f32 v[2:3], v[14:15], v[22:23] op_sel_hi:[1,0]
	v_pk_mul_f32 v[4:5], v[16:17], v[22:23] op_sel_hi:[1,0]
	global_store_dwordx4 v[150:151], v[18:21], off offset:352
	global_store_dwordx4 v[150:151], v[2:5], off offset:480
	v_lshl_add_u64 v[86:87], s[6:7], 0, v[158:159]
	global_load_dwordx4 v[2:5], v[86:87], off
	global_load_dwordx4 v[6:9], v[154:155], off
	global_load_dwordx4 v[10:13], v[156:157], off
	v_lshlrev_b32_e32 v14, 1, v166
	v_mov_b32_e32 v15, v1
	v_lshl_add_u64 v[16:17], s[0:1], 0, v[152:153]
	v_lshl_add_u64 v[14:15], v[16:17], 0, v[14:15]
	s_movk_i32 s0, 0x2000
	global_load_dwordx4 v[114:117], v[14:15], off
	global_load_dwordx4 v[118:121], v[14:15], off offset:32
	global_load_dwordx4 v[122:125], v[14:15], off offset:64
	global_load_dwordx4 v[126:129], v[14:15], off offset:96
	s_nop 0
	global_load_dwordx4 v[14:17], v[154:155], off offset:128
	global_load_dwordx4 v[18:21], v[156:157], off offset:128
	v_readlane_b32 s17, v252, 7
	v_readlane_b32 s22, v252, 12
	v_readlane_b32 s23, v252, 13
	s_waitcnt vmcnt(8)
	ds_write_b128 v143, v[2:5]
	s_waitcnt vmcnt(7)
	ds_write2_b64 v170, v[6:7], v[8:9] offset1:1
	s_waitcnt vmcnt(6)
	ds_write2_b64 v171, v[10:11], v[12:13] offset1:1
	v_add_co_u32_e32 v2, vcc, s0, v86
	s_nop 1
	v_addc_co_u32_e32 v3, vcc, 0, v87, vcc
	global_load_dwordx4 v[82:85], v[2:3], off
	s_waitcnt lgkmcnt(0)
	s_barrier
; template <int DQK, int MODE, bool PIPE>
; DI void attn_core(const u16* __restrict__ Qg, const u16* __restrict__ Kg, const u16* __restrict__ Vtg, int ntiles,
;                   int kr_lo, int rs, int r_q, int c_q, int cs, const float* biasL, char* lds, f32x16 (&o)[4], float& l_out, int tid) {
;     ...
;     if (MODE == 0) {
;       constexpr int R = 4, NF = 2 * NKS;
;       const unsigned kaddr = (unsigned)(size_t)kb;
;       bf16x8 f[R];
;       SBAR();
;       f[0] = lds_rd128<0>(kaddr); f[1] = lds_rd128<32 * KSTR>(kaddr); f[2] = lds_rd128<32>(kaddr); f[3] = lds_rd128<32 * KSTR + 32>(kaddr);
;       SBAR();
;       __builtin_amdgcn_s_setprio(1);
;       QkStep<DQK, 0, NF, R>::run(kaddr, f, qf, p0, p1, negm);
;       __builtin_amdgcn_s_setprio(0);
;     ...
;     asm volatile("s_nop 7\n\ts_nop 7\n\ts_nop 7" ::: "memory");
;     if (!NEGM && __any(m != 0.f)) {
; #pragma unroll
;       for (int i = 0; i < 16; ++i) {
;         asm("v_sub_f32 %0, %1, %2" : "=v"(p0[i]) : "v"(p0[i]), "v"(m));
;         asm("v_sub_f32 %0, %1, %2" : "=v"(p1[i]) : "v"(p1[i]), "v"(m));
;       }
;     }
;     float tmx;
;     {
;       float u[11];
; #pragma unroll
;       for (int i = 0; i < 5; ++i) {
;         asm("v_max3_f32 %0, %1, %2, %3" : "=v"(u[2 * i]) : "v"(p0[3 * i]), "v"(p0[3 * i + 1]), "v"(p0[3 * i + 2]));
;         asm("v_max3_f32 %0, %1, %2, %3" : "=v"(u[2 * i + 1]) : "v"(p1[3 * i]), "v"(p1[3 * i + 1]), "v"(p1[3 * i + 2]));
;       }
;       asm("v_max3_f32 %0, %1, %2, %3" : "=v"(u[10]) : "v"(p0[15]), "v"(p1[15]), "v"(u[0]));
;       float w0, w1, w2, w3;
;       asm("v_max3_f32 %0, %1, %2, %3" : "=v"(w0) : "v"(u[1]), "v"(u[2]), "v"(u[3]));
;       asm("v_max3_f32 %0, %1, %2, %3" : "=v"(w1) : "v"(u[4]), "v"(u[5]), "v"(u[6]));
;       asm("v_max3_f32 %0, %1, %2, %3" : "=v"(w2) : "v"(u[7]), "v"(u[8]), "v"(u[9]));
;       asm("v_max3_f32 %0, %1, %2, %3" : "=v"(w3) : "v"(u[10]), "v"(w0), "v"(w1));
;       asm("v_max_f32 %0, %1, %2" : "=v"(tmx) : "v"(w2), "v"(w3));
;     }
;     const bool t0 = (t == 0);
;     if (__any(tmx > THR || (t0 && tmx < -THR))) {
;       tmx = fmaxf(tmx, __shfl_xor(tmx, 32));
;       const float delta = t0 ? tmx : fmaxf(tmx, 0.f);
;       const float alpha = __builtin_amdgcn_exp2f(-fmaxf(delta, 0.f));
;       m += delta; l *= alpha;
; #pragma unroll
;       for (int d = 0; d < 4; ++d)
; #pragma unroll
;         for (int i = 0; i < 16; ++i) o[d][i] *= alpha;
	global_load_dwordx4 v[130:133], v[154:155], off offset:256
	global_load_dwordx4 v[134:137], v[156:157], off offset:256
	s_waitcnt vmcnt(4)
	ds_write2_b64 v173, v[14:15], v[16:17] offset1:1
	s_waitcnt vmcnt(3)
	ds_write2_b64 v172, v[18:19], v[20:21] offset1:1
	ds_read_b128 v[2:5], v174 offset:0
	ds_read_b128 v[6:9], v174 offset:0x1200
	ds_read_b128 v[10:13], v174 offset:32
	ds_read_b128 v[14:17], v174 offset:0x1220
	s_setprio 1
	s_waitcnt lgkmcnt(3)
	v_mfma_f32_32x32x16_bf16 v[18:33], v[2:5], v[114:117], 0
	ds_read_b128 v[2:5], v174 offset:64
	s_waitcnt lgkmcnt(3)
	v_mfma_f32_32x32x16_bf16 v[36:51], v[6:9], v[114:117], 0
	ds_read_b128 v[6:9], v174 offset:0x1240
	s_waitcnt lgkmcnt(3)
	v_mfma_f32_32x32x16_bf16 v[18:33], v[10:13], v[118:121], v[18:33]
	ds_read_b128 v[10:13], v174 offset:0x60
	s_waitcnt lgkmcnt(3)
	v_mfma_f32_32x32x16_bf16 v[36:51], v[14:17], v[118:121], v[36:51]
	ds_read_b128 v[14:17], v174 offset:0x1260
	s_waitcnt lgkmcnt(3)
	v_mfma_f32_32x32x16_bf16 v[18:33], v[2:5], v[122:125], v[18:33]
	s_waitcnt lgkmcnt(2)
	v_mfma_f32_32x32x16_bf16 v[36:51], v[6:9], v[122:125], v[36:51]
	s_waitcnt lgkmcnt(1)
	v_mfma_f32_32x32x16_bf16 v[18:33], v[10:13], v[126:129], v[18:33]
	s_waitcnt lgkmcnt(0)
	v_mfma_f32_32x32x16_bf16 v[36:51], v[14:17], v[126:129], v[36:51]
	s_setprio 0
	v_max3_f32 v2, v18, v19, v20
	s_nop 7
	s_nop 7
	s_nop 7
	v_max3_f32 v3, v36, v37, v38
	v_max3_f32 v4, v21, v22, v23
	v_max3_f32 v5, v39, v40, v41
	v_max3_f32 v6, v24, v25, v26
	s_nop 0
	v_max3_f32 v2, v33, v51, v2
	v_max3_f32 v7, v42, v43, v44
	v_max3_f32 v8, v27, v28, v29
	v_max3_f32 v9, v45, v46, v47
	v_max3_f32 v3, v3, v4, v5
	v_max3_f32 v10, v30, v31, v32
	v_max3_f32 v11, v48, v49, v50
	s_nop 0
	v_max3_f32 v4, v6, v7, v8
	v_max3_f32 v5, v9, v10, v11
	s_nop 0
	v_max3_f32 v2, v2, v3, v4
	s_nop 0
	v_max_f32 v2, v5, v2
	s_nop 0
	v_cmp_gt_f32_e64 vcc, |v2|, s66
	s_cbranch_vccz .LBB0_852
	ds_bpermute_b32 v3, v162, v2
	v_max_f32_e32 v2, v2, v2
	s_waitcnt lgkmcnt(0)
	v_max_f32_e32 v3, v3, v3
	v_max_f32_e32 v4, v2, v3
	v_max_f32_e32 v2, 0, v4
	v_exp_f32_e64 v2, -v2
	v_add_f32_e32 v154, 0, v4
	v_pk_add_f32 v[18:19], v[18:19], v[4:5] op_sel_hi:[1,0] neg_lo:[0,1] neg_hi:[0,1]
	v_pk_add_f32 v[36:37], v[36:37], v[4:5] op_sel_hi:[1,0] neg_lo:[0,1] neg_hi:[0,1]
	v_pk_add_f32 v[20:21], v[20:21], v[4:5] op_sel_hi:[1,0] neg_lo:[0,1] neg_hi:[0,1]
	v_pk_add_f32 v[38:39], v[38:39], v[4:5] op_sel_hi:[1,0] neg_lo:[0,1] neg_hi:[0,1]
	v_pk_add_f32 v[22:23], v[22:23], v[4:5] op_sel_hi:[1,0] neg_lo:[0,1] neg_hi:[0,1]
	v_mul_f32_e32 v2, 0, v2
	v_pk_add_f32 v[40:41], v[40:41], v[4:5] op_sel_hi:[1,0] neg_lo:[0,1] neg_hi:[0,1]
	v_pk_add_f32 v[24:25], v[24:25], v[4:5] op_sel_hi:[1,0] neg_lo:[0,1] neg_hi:[0,1]
	v_pk_add_f32 v[42:43], v[42:43], v[4:5] op_sel_hi:[1,0] neg_lo:[0,1] neg_hi:[0,1]
	v_pk_add_f32 v[26:27], v[26:27], v[4:5] op_sel_hi:[1,0] neg_lo:[0,1] neg_hi:[0,1]
	v_pk_add_f32 v[44:45], v[44:45], v[4:5] op_sel_hi:[1,0] neg_lo:[0,1] neg_hi:[0,1]
	v_pk_add_f32 v[28:29], v[28:29], v[4:5] op_sel_hi:[1,0] neg_lo:[0,1] neg_hi:[0,1]
	v_pk_add_f32 v[46:47], v[46:47], v[4:5] op_sel_hi:[1,0] neg_lo:[0,1] neg_hi:[0,1]
	v_pk_add_f32 v[30:31], v[30:31], v[4:5] op_sel_hi:[1,0] neg_lo:[0,1] neg_hi:[0,1]
	v_pk_add_f32 v[48:49], v[48:49], v[4:5] op_sel_hi:[1,0] neg_lo:[0,1] neg_hi:[0,1]
	v_pk_add_f32 v[32:33], v[32:33], v[4:5] op_sel_hi:[1,0] neg_lo:[0,1] neg_hi:[0,1]
	v_pk_add_f32 v[50:51], v[50:51], v[4:5] op_sel_hi:[1,0] neg_lo:[0,1] neg_hi:[0,1]
	v_xor_b32_e32 v34, 0x80000000, v154
	s_branch .LBB0_853

; #define SBAR() __builtin_amdgcn_sched_barrier(0)
; template <int DQK, int MODE, bool PIPE>
; DI void attn_core(const u16* __restrict__ Qg, const u16* __restrict__ Kg, const u16* __restrict__ Vtg, int ntiles,
;                   int kr_lo, int rs, int r_q, int c_q, int cs, const float* biasL, char* lds, f32x16 (&o)[4], float& l_out, int tid) {
;     ...
;     for (int i = 0; i < 16; ++i) { p0[i] = __builtin_amdgcn_exp2f(p0[i]); p1[i] = __builtin_amdgcn_exp2f(p1[i]); ps += p0[i] + p1[i]; }
;     l += ps;
;     const char* vb = lds + (t & 1) * A_BUF + A_VOFF + r32 * 136 + h * 8;
;     {
;       bf16x8 pfc;
;       constexpr int R = PV_RING;
;       const unsigned vaddr = (unsigned)(size_t)vb;
;       s16x4 vlo[R], vhi[R];
;       SBAR();
;       vlo[0] = lds_rd64<0>(vaddr); vhi[0] = lds_rd64<16>(vaddr);
;       vlo[1] = lds_rd64<32 * 136>(vaddr); vhi[1] = lds_rd64<32 * 136 + 16>(vaddr);
;       if (R > 2) { vlo[2 % R] = lds_rd64<64 * 136>(vaddr); vhi[2 % R] = lds_rd64<64 * 136 + 16>(vaddr); }
;       if (R > 3) { vlo[3 % R] = lds_rd64<96 * 136>(vaddr); vhi[3 % R] = lds_rd64<96 * 136 + 16>(vaddr); }
;       SBAR();
;       __builtin_amdgcn_s_setprio(1);
;       PvStep<0, 16, R>::run(vaddr, vlo, vhi, p0, p1, pfc, o);
;       __builtin_amdgcn_s_setprio(0);
;     ...
;       if (t + 2 < ntiles) swriteK(t & 1);
;       if (t + 3 < ntiles) gloadK(t + 3);
;     } else {
;       if (is_active(t)) { qk(t, c0, c1); sm_pv(t, c0, c1); }
;       if (t + 1 < ntiles) swriteK((t + 1) & 1);
;       if (t + 2 < ntiles) gloadK(t + 2);
.LBB0_860:
	v_exp_f32_e32 v82, v82
	v_exp_f32_e32 v98, v98
	v_exp_f32_e32 v83, v83
	v_exp_f32_e32 v99, v99
	v_exp_f32_e32 v84, v84
	v_exp_f32_e32 v100, v100
	v_exp_f32_e32 v85, v85
	v_exp_f32_e32 v101, v101
	v_exp_f32_e32 v86, v86
	v_exp_f32_e32 v102, v102
	v_exp_f32_e32 v87, v87
	v_exp_f32_e32 v103, v103
	v_exp_f32_e32 v88, v88
	v_exp_f32_e32 v104, v104
	v_exp_f32_e32 v89, v89
	v_exp_f32_e32 v105, v105
	v_exp_f32_e32 v90, v90
	v_exp_f32_e32 v106, v106
	v_exp_f32_e32 v91, v91
	v_exp_f32_e32 v107, v107
	v_exp_f32_e32 v92, v92
	v_exp_f32_e32 v108, v108
	v_exp_f32_e32 v93, v93
	v_exp_f32_e32 v109, v109
	v_exp_f32_e32 v94, v94
	v_exp_f32_e32 v110, v110
	v_exp_f32_e32 v95, v95
	v_exp_f32_e32 v111, v111
	v_exp_f32_e32 v96, v96
	v_exp_f32_e32 v112, v112
	v_exp_f32_e32 v97, v97
	v_exp_f32_e32 v113, v113
	v_add_u32_e32 v156, s12, v168
	v_add3_u32 v160, v156, v166, s33
	ds_read_b64 v[156:157], v160 offset:0
	ds_read_b64 v[158:159], v160 offset:16
	ds_read_b64 v[170:171], v160 offset:0x1100
	ds_read_b64 v[172:173], v160 offset:0x1110
	ds_read_b64 v[174:175], v160 offset:0x2200
	ds_read_b64 v[176:177], v160 offset:0x2210
	ds_read_b64 v[216:217], v160 offset:0x3300
	ds_read_b64 v[218:219], v160 offset:0x3310
	s_setprio 1
	s_waitcnt lgkmcnt(4)
	v_cvt_pk_bf16_f32 v220, v82, v83
	v_cvt_pk_bf16_f32 v221, v84, v85
	v_cvt_pk_bf16_f32 v222, v86, v87
	v_cvt_pk_bf16_f32 v223, v88, v89
	s_nop 1
	v_mfma_f32_32x32x16_bf16 v[66:81], v[156:159], v[220:223], v[66:81]
	ds_read_b64 v[156:157], v160 offset:32
	ds_read_b64 v[158:159], v160 offset:48
	v_mfma_f32_32x32x16_bf16 v[50:65], v[170:173], v[220:223], v[50:65]
	ds_read_b64 v[170:171], v160 offset:0x1120
	ds_read_b64 v[172:173], v160 offset:0x1130
	s_waitcnt lgkmcnt(4)
	v_mfma_f32_32x32x16_bf16 v[18:33], v[174:177], v[220:223], v[18:33]
	ds_read_b64 v[174:175], v160 offset:0x2220
	ds_read_b64 v[176:177], v160 offset:0x2230
	v_mfma_f32_32x32x16_bf16 v[2:17], v[216:219], v[220:223], v[2:17]
	ds_read_b64 v[216:217], v160 offset:0x3320
	ds_read_b64 v[218:219], v160 offset:0x3330
	s_waitcnt lgkmcnt(4)
	v_cvt_pk_bf16_f32 v220, v90, v91
	v_cvt_pk_bf16_f32 v221, v92, v93
	v_cvt_pk_bf16_f32 v222, v94, v95
	v_cvt_pk_bf16_f32 v223, v96, v97
	s_nop 1
	v_mfma_f32_32x32x16_bf16 v[66:81], v[156:159], v[220:223], v[66:81]
	ds_read_b64 v[156:157], v160 offset:64
	ds_read_b64 v[158:159], v160 offset:0x50
	v_mfma_f32_32x32x16_bf16 v[50:65], v[170:173], v[220:223], v[50:65]
	ds_read_b64 v[170:171], v160 offset:0x1140
	ds_read_b64 v[172:173], v160 offset:0x1150
	s_waitcnt lgkmcnt(4)
	v_mfma_f32_32x32x16_bf16 v[18:33], v[174:177], v[220:223], v[18:33]
	ds_read_b64 v[174:175], v160 offset:0x2240
	ds_read_b64 v[176:177], v160 offset:0x2250
	v_mfma_f32_32x32x16_bf16 v[2:17], v[216:219], v[220:223], v[2:17]
	ds_read_b64 v[216:217], v160 offset:0x3340
	ds_read_b64 v[218:219], v160 offset:0x3350
	s_waitcnt lgkmcnt(4)
	v_cvt_pk_bf16_f32 v220, v98, v99
	v_cvt_pk_bf16_f32 v221, v100, v101
	v_cvt_pk_bf16_f32 v222, v102, v103
	v_cvt_pk_bf16_f32 v223, v104, v105
	s_nop 1
	v_mfma_f32_32x32x16_bf16 v[66:81], v[156:159], v[220:223], v[66:81]
	ds_read_b64 v[156:157], v160 offset:0x60
	ds_read_b64 v[158:159], v160 offset:0x70
	v_mfma_f32_32x32x16_bf16 v[50:65], v[170:173], v[220:223], v[50:65]
	ds_read_b64 v[170:171], v160 offset:0x1160
	ds_read_b64 v[172:173], v160 offset:0x1170
	s_waitcnt lgkmcnt(4)
	v_mfma_f32_32x32x16_bf16 v[18:33], v[174:177], v[220:223], v[18:33]
	ds_read_b64 v[174:175], v160 offset:0x2260
	ds_read_b64 v[176:177], v160 offset:0x2270
	v_mfma_f32_32x32x16_bf16 v[2:17], v[216:219], v[220:223], v[2:17]
	ds_read_b64 v[216:217], v160 offset:0x3360
	ds_read_b64 v[218:219], v160 offset:0x3370
	s_waitcnt lgkmcnt(4)
	v_cvt_pk_bf16_f32 v220, v106, v107
	v_cvt_pk_bf16_f32 v221, v108, v109
	v_cvt_pk_bf16_f32 v222, v110, v111
	v_cvt_pk_bf16_f32 v223, v112, v113
	s_nop 1
	v_mfma_f32_32x32x16_bf16 v[66:81], v[156:159], v[220:223], v[66:81]
	v_mfma_f32_32x32x16_bf16 v[50:65], v[170:173], v[220:223], v[50:65]
	s_waitcnt lgkmcnt(0)
	v_mfma_f32_32x32x16_bf16 v[18:33], v[174:177], v[220:223], v[18:33]
	v_mfma_f32_32x32x16_bf16 v[2:17], v[216:219], v[220:223], v[2:17]
	s_andn2_b64 vcc, exec, s[0:1]
	s_cbranch_vccnz .LBB0_862
	s_bitcmp1_b32 s11, 0
	s_cselect_b32 s0, 0xa800, 0
	v_add_u32_e32 v156, s0, v143
	s_waitcnt vmcnt(0)
	ds_write_b128 v156, v[138:141]

;     ...
;       const float inv2 = p.lam[layer] / l;
;       float ss = 0.f;
; #pragma unroll
;       for (int d = 0; d < 4; ++d)
; #pragma unroll
;         for (int g = 0; g < 4; ++g) {
;           const float4 a = *(const float4*)(d1 + 32 * d + 8 * g);
;           o[d][4 * g] = a.x - o[d][4 * g] * inv2; o[d][4 * g + 1] = a.y - o[d][4 * g + 1] * inv2;
;           o[d][4 * g + 2] = a.z - o[d][4 * g + 2] * inv2; o[d][4 * g + 3] = a.w - o[d][4 * g + 3] * inv2;
;           ss += o[d][4 * g] * o[d][4 * g] + o[d][4 * g + 1] * o[d][4 * g + 1] + o[d][4 * g + 2] * o[d][4 * g + 2] + o[d][4 * g + 3] * o[d][4 * g + 3];
;         }
;       ss += __shfl_xor(ss, 32);
.LBB0_866:
	s_setprio 0
	global_load_dword v34, v[212:213], off
	ds_bpermute_b32 v0, v162, v155
	s_waitcnt lgkmcnt(0)
	v_add_f32_e32 v0, v155, v0
	s_waitcnt vmcnt(0)
	v_div_scale_f32 v35, s[0:1], v0, v0, v34
	v_rcp_f32_e32 v36, v35
	s_mov_b32 s0, 0x800000
	v_fma_f32 v37, -v35, v36, 1.0
	v_fmac_f32_e32 v36, v37, v36
	v_div_scale_f32 v37, vcc, v34, v0, v34
	v_mul_f32_e32 v38, v37, v36
	v_fma_f32 v39, -v35, v38, v37
	v_fmac_f32_e32 v38, v39, v36
	v_fma_f32 v35, -v35, v38, v37
	v_div_fmas_f32 v35, v35, v36, v38
	v_div_fixup_f32 v0, v35, v0, v34
	global_load_dwordx4 v[34:37], v[150:151], off
	s_waitcnt vmcnt(0)
	v_pk_fma_f32 v[88:89], v[66:67], v[0:1], v[34:35] op_sel_hi:[1,0,1] neg_lo:[1,0,0] neg_hi:[1,0,0]
	v_pk_fma_f32 v[90:91], v[68:69], v[0:1], v[36:37] op_sel_hi:[1,0,1] neg_lo:[1,0,0] neg_hi:[1,0,0]
	global_load_dwordx4 v[34:37], v[150:151], off offset:32
	v_pk_mul_f32 v[94:95], v[88:89], v[88:89]
	v_pk_mul_f32 v[92:93], v[90:91], v[90:91]
	s_waitcnt vmcnt(0)
	v_pk_fma_f32 v[86:87], v[70:71], v[0:1], v[34:35] op_sel_hi:[1,0,1] neg_lo:[1,0,0] neg_hi:[1,0,0]
	v_pk_fma_f32 v[84:85], v[72:73], v[0:1], v[36:37] op_sel_hi:[1,0,1] neg_lo:[1,0,0] neg_hi:[1,0,0]
	global_load_dwordx4 v[34:37], v[150:151], off offset:64
	v_pk_mul_f32 v[98:99], v[86:87], v[86:87]
	v_pk_mul_f32 v[96:97], v[84:85], v[84:85]
	s_waitcnt vmcnt(0)
	v_pk_fma_f32 v[82:83], v[74:75], v[0:1], v[34:35] op_sel_hi:[1,0,1] neg_lo:[1,0,0] neg_hi:[1,0,0]
	v_pk_fma_f32 v[74:75], v[76:77], v[0:1], v[36:37] op_sel_hi:[1,0,1] neg_lo:[1,0,0] neg_hi:[1,0,0]
	global_load_dwordx4 v[34:37], v[150:151], off offset:96
	v_pk_mul_f32 v[100:101], v[82:83], v[82:83]
	v_pk_mul_f32 v[76:77], v[74:75], v[74:75]
	s_waitcnt vmcnt(0)
	v_pk_fma_f32 v[72:73], v[78:79], v[0:1], v[34:35] op_sel_hi:[1,0,1] neg_lo:[1,0,0] neg_hi:[1,0,0]
	v_pk_fma_f32 v[70:71], v[80:81], v[0:1], v[36:37] op_sel_hi:[1,0,1] neg_lo:[1,0,0] neg_hi:[1,0,0]
	global_load_dwordx4 v[34:37], v[150:151], off offset:128
	v_pk_mul_f32 v[80:81], v[72:73], v[72:73]
	v_pk_mul_f32 v[78:79], v[70:71], v[70:71]
	s_waitcnt vmcnt(0)
	v_pk_fma_f32 v[68:69], v[50:51], v[0:1], v[34:35] op_sel_hi:[1,0,1] neg_lo:[1,0,0] neg_hi:[1,0,0]
	v_pk_fma_f32 v[66:67], v[52:53], v[0:1], v[36:37] op_sel_hi:[1,0,1] neg_lo:[1,0,0] neg_hi:[1,0,0]
	global_load_dwordx4 v[34:37], v[150:151], off offset:160
	v_pk_mul_f32 v[104:105], v[68:69], v[68:69]
	v_pk_mul_f32 v[102:103], v[66:67], v[66:67]
	s_waitcnt vmcnt(0)
	v_pk_fma_f32 v[52:53], v[54:55], v[0:1], v[34:35] op_sel_hi:[1,0,1] neg_lo:[1,0,0] neg_hi:[1,0,0]
	v_pk_fma_f32 v[50:51], v[56:57], v[0:1], v[36:37] op_sel_hi:[1,0,1] neg_lo:[1,0,0] neg_hi:[1,0,0]
	global_load_dwordx4 v[34:37], v[150:151], off offset:192
	v_pk_mul_f32 v[56:57], v[52:53], v[52:53]
	v_pk_mul_f32 v[54:55], v[50:51], v[50:51]
	s_waitcnt vmcnt(0)
	v_pk_fma_f32 v[48:49], v[58:59], v[0:1], v[34:35] op_sel_hi:[1,0,1] neg_lo:[1,0,0] neg_hi:[1,0,0]
	v_pk_fma_f32 v[44:45], v[60:61], v[0:1], v[36:37] op_sel_hi:[1,0,1] neg_lo:[1,0,0] neg_hi:[1,0,0]
	global_load_dwordx4 v[34:37], v[150:151], off offset:224
	v_mov_b32_e32 v40, v49
	s_waitcnt vmcnt(0)
	v_pk_fma_f32 v[38:39], v[62:63], v[0:1], v[34:35] op_sel_hi:[1,0,1] neg_lo:[1,0,0] neg_hi:[1,0,0]
	s_nop 0
	v_mov_b32_e32 v41, v39
	v_pk_fma_f32 v[36:37], v[64:65], v[0:1], v[36:37] op_sel_hi:[1,0,1] neg_lo:[1,0,0] neg_hi:[1,0,0]
	v_mov_b32_e32 v34, v48
	v_mov_b32_e32 v35, v38
	v_pk_mul_f32 v[40:41], v[40:41], v[40:41]
	global_load_dwordx4 v[60:63], v[150:151], off offset:384
	v_pk_fma_f32 v[34:35], v[34:35], v[34:35], v[40:41]
	v_mov_b32_e32 v40, v44
	v_mov_b32_e32 v41, v36
	v_pk_fma_f32 v[34:35], v[40:41], v[40:41], v[34:35]
	v_mov_b32_e32 v40, v45
	v_mov_b32_e32 v41, v37
	v_pk_fma_f32 v[58:59], v[40:41], v[40:41], v[34:35]
	global_load_dwordx4 v[40:43], v[150:151], off offset:256
	s_waitcnt vmcnt(0)
	v_pk_fma_f32 v[46:47], v[18:19], v[0:1], v[40:41] op_sel_hi:[1,0,1] neg_lo:[1,0,0] neg_hi:[1,0,0]
	v_pk_fma_f32 v[42:43], v[20:21], v[0:1], v[42:43] op_sel_hi:[1,0,1] neg_lo:[1,0,0] neg_hi:[1,0,0]
	global_load_dwordx4 v[18:21], v[150:151], off offset:288
	s_waitcnt vmcnt(0)
	v_pk_fma_f32 v[34:35], v[22:23], v[0:1], v[18:19] op_sel_hi:[1,0,1] neg_lo:[1,0,0] neg_hi:[1,0,0]
	v_pk_fma_f32 v[22:23], v[24:25], v[0:1], v[20:21] op_sel_hi:[1,0,1] neg_lo:[1,0,0] neg_hi:[1,0,0]
	v_mov_b32_e32 v20, v47
	v_mov_b32_e32 v21, v35
	v_mov_b32_e32 v18, v46
	v_mov_b32_e32 v19, v34
	v_pk_mul_f32 v[20:21], v[20:21], v[20:21]
	s_nop 0
	v_pk_fma_f32 v[18:19], v[18:19], v[18:19], v[20:21]
	v_mov_b32_e32 v20, v42
	v_mov_b32_e32 v21, v22
	v_pk_fma_f32 v[18:19], v[20:21], v[20:21], v[18:19]
	v_mov_b32_e32 v20, v43
	v_mov_b32_e32 v21, v23
	v_pk_fma_f32 v[64:65], v[20:21], v[20:21], v[18:19]
	global_load_dwordx4 v[18:21], v[150:151], off offset:320
	s_waitcnt vmcnt(0)
; DI unsigned pk2(float a, float b) { f32v2 f = {a, b}; bf16v2 r = __builtin_convertvector(f, bf16v2); return __builtin_bit_cast(unsigned, r); }
; DI float bflo(unsigned w) { return __uint_as_float(w << 16); }
; DI float bfhi(unsigned w) { return __uint_as_float(w & 0xffff0000u); }
; DI void store_gated(const Params& p, int R, int colbase, f32x16 (&o)[4], float mult, const float* wv, int h) {
; #pragma unroll
;   for (int d0 = 0; d0 < 4; ++d0)
; #pragma unroll
;     for (int g = 0; g < 4; ++g) {
;       const int dv = 32 * d0 + 8 * g + 4 * h;
;       const size_t off = (size_t)R * DM + colbase + dv;
;       const u32x2 gg = *(const u32x2*)(p.Gs + off);
;       float v0 = o[d0][4 * g] * mult, v1 = o[d0][4 * g + 1] * mult, v2 = o[d0][4 * g + 2] * mult, v3 = o[d0][4 * g + 3] * mult;
;       if (wv) { v0 *= wv[dv]; v1 *= wv[dv + 1]; v2 *= wv[dv + 2]; v3 *= wv[dv + 3]; }
;       u32x2 ov = {pk2(v0 * bflo(gg[0]), v1 * bfhi(gg[0])), pk2(v2 * bflo(gg[1]), v3 * bfhi(gg[1]))};
;       *(u32x2*)(p.H + off) = ov;
;       __builtin_amdgcn_sched_barrier(0);
;     }
; }
;     ...
;           ss += o[d][4 * g] * o[d][4 * g] + o[d][4 * g + 1] * o[d][4 * g + 1] + o[d][4 * g + 2] * o[d][4 * g + 2] + o[d][4 * g + 3] * o[d][4 * g + 3];
;         }
;       ss += __shfl_xor(ss, 32);
;       const float mult = rsqrtf(ss * (1.f / 128.f) + EPS) * p.lam[4 + layer];
;       store_gated(p, q0 + wid * 32 + r32, 1408 + hd * 128, o, mult, p.subln + layer * 128, h);
	v_pk_fma_f32 v[40:41], v[26:27], v[0:1], v[18:19] op_sel_hi:[1,0,1] neg_lo:[1,0,0] neg_hi:[1,0,0]
	v_pk_fma_f32 v[28:29], v[28:29], v[0:1], v[20:21] op_sel_hi:[1,0,1] neg_lo:[1,0,0] neg_hi:[1,0,0]
	global_load_dwordx4 v[18:21], v[150:151], off offset:352
	v_mov_b32_e32 v26, v41
	s_waitcnt vmcnt(0)
	v_pk_fma_f32 v[24:25], v[30:31], v[0:1], v[18:19] op_sel_hi:[1,0,1] neg_lo:[1,0,0] neg_hi:[1,0,0]
	v_pk_fma_f32 v[18:19], v[32:33], v[0:1], v[20:21] op_sel_hi:[1,0,1] neg_lo:[1,0,0] neg_hi:[1,0,0]
	v_pk_fma_f32 v[32:33], v[2:3], v[0:1], v[60:61] op_sel_hi:[1,0,1] neg_lo:[1,0,0] neg_hi:[1,0,0]
	v_pk_fma_f32 v[30:31], v[4:5], v[0:1], v[62:63] op_sel_hi:[1,0,1] neg_lo:[1,0,0] neg_hi:[1,0,0]
	global_load_dwordx4 v[2:5], v[150:151], off offset:416
	v_mov_b32_e32 v27, v25
	v_mov_b32_e32 v20, v40
	v_mov_b32_e32 v21, v24
	v_pk_mul_f32 v[26:27], v[26:27], v[26:27]
	s_nop 0
	v_pk_fma_f32 v[20:21], v[20:21], v[20:21], v[26:27]
	v_mov_b32_e32 v26, v28
	v_mov_b32_e32 v27, v18
	v_pk_fma_f32 v[20:21], v[26:27], v[26:27], v[20:21]
	v_mov_b32_e32 v26, v29
	v_mov_b32_e32 v27, v19
	v_pk_fma_f32 v[106:107], v[26:27], v[26:27], v[20:21]
	s_waitcnt vmcnt(0)
	v_pk_fma_f32 v[26:27], v[6:7], v[0:1], v[2:3] op_sel_hi:[1,0,1] neg_lo:[1,0,0] neg_hi:[1,0,0]
	v_pk_fma_f32 v[20:21], v[8:9], v[0:1], v[4:5] op_sel_hi:[1,0,1] neg_lo:[1,0,0] neg_hi:[1,0,0]
	v_mov_b32_e32 v4, v33
	v_mov_b32_e32 v5, v27
	v_mov_b32_e32 v2, v32
	v_mov_b32_e32 v3, v26
	v_pk_mul_f32 v[4:5], v[4:5], v[4:5]
	s_nop 0
	v_pk_fma_f32 v[2:3], v[2:3], v[2:3], v[4:5]
	v_mov_b32_e32 v4, v30
	v_mov_b32_e32 v5, v20
	v_pk_fma_f32 v[2:3], v[4:5], v[4:5], v[2:3]
	v_mov_b32_e32 v4, v31
	v_mov_b32_e32 v5, v21
	v_pk_fma_f32 v[60:61], v[4:5], v[4:5], v[2:3]
	global_load_dwordx4 v[2:5], v[150:151], off offset:448
	s_waitcnt vmcnt(0)
	v_pk_fma_f32 v[8:9], v[10:11], v[0:1], v[2:3] op_sel_hi:[1,0,1] neg_lo:[1,0,0] neg_hi:[1,0,0]
	v_pk_fma_f32 v[6:7], v[12:13], v[0:1], v[4:5] op_sel_hi:[1,0,1] neg_lo:[1,0,0] neg_hi:[1,0,0]
	global_load_dwordx4 v[10:13], v[150:151], off offset:480
	s_waitcnt vmcnt(0)
	v_pk_fma_f32 v[4:5], v[14:15], v[0:1], v[10:11] op_sel_hi:[1,0,1] neg_lo:[1,0,0] neg_hi:[1,0,0]
	v_pk_fma_f32 v[2:3], v[16:17], v[0:1], v[12:13] op_sel_hi:[1,0,1] neg_lo:[1,0,0] neg_hi:[1,0,0]
	v_mov_b32_e32 v12, v9
	v_mov_b32_e32 v13, v5
	v_mov_b32_e32 v10, v8
	v_mov_b32_e32 v11, v4
	v_pk_mul_f32 v[12:13], v[12:13], v[12:13]
	v_add_f32_e32 v0, v98, v99
	v_pk_fma_f32 v[10:11], v[10:11], v[10:11], v[12:13]
	v_mov_b32_e32 v12, v6
	v_mov_b32_e32 v13, v2
	v_pk_fma_f32 v[10:11], v[12:13], v[12:13], v[10:11]
	v_mov_b32_e32 v12, v7
	v_mov_b32_e32 v13, v3
	v_pk_fma_f32 v[10:11], v[12:13], v[12:13], v[10:11]
	v_add_f32_e32 v12, v94, v95
	v_add_f32_e32 v0, v96, v0
	v_add_f32_e32 v12, v92, v12
	v_add_f32_e32 v0, v97, v0
	v_add_f32_e32 v12, v93, v12
	v_add_f32_e32 v0, v12, v0
	v_add_f32_e32 v12, v100, v101
	v_add_f32_e32 v12, v76, v12
	v_add_f32_e32 v12, v77, v12
	v_add_f32_e32 v0, v0, v12
	v_add_f32_e32 v12, v80, v81
	v_add_f32_e32 v12, v78, v12
	v_add_f32_e32 v12, v79, v12
	v_add_f32_e32 v0, v0, v12
	v_add_f32_e32 v12, v104, v105
	v_add_f32_e32 v12, v102, v12
	v_add_f32_e32 v12, v103, v12
	v_add_f32_e32 v0, v0, v12
	v_add_f32_e32 v12, v56, v57
	v_add_f32_e32 v12, v54, v12
	v_add_f32_e32 v12, v55, v12
	v_add_f32_e32 v0, v0, v12
	v_add_f32_e32 v0, v0, v58
	v_add_f32_e32 v0, v0, v59
	v_add_f32_e32 v0, v0, v64
	v_add_f32_e32 v0, v0, v65
	v_add_f32_e32 v0, v0, v106
	v_add_f32_e32 v0, v0, v107
	v_add_f32_e32 v0, v0, v60
	v_add_f32_e32 v0, v0, v61
	v_add_f32_e32 v0, v0, v10
	v_add_f32_e32 v0, v0, v11
	ds_bpermute_b32 v10, v162, v0
	s_waitcnt lgkmcnt(0)
	v_add_f32_e32 v0, v0, v10
	v_fmamk_f32 v0, v0, 0x3c000000, v187
	v_cmp_gt_f32_e32 vcc, s0, v0
	v_mul_f32_e32 v10, 0x4b800000, v0
	s_lshl_b32 s0, s8, 7
	v_cndmask_b32_e32 v0, v0, v10, vcc
	v_rsq_f32_e32 v0, v0
	s_ashr_i32 s1, s0, 31
	v_mul_f32_e32 v10, 0x45800000, v0
	v_cndmask_b32_e32 v0, v0, v10, vcc
	global_load_dword v10, v[212:213], off offset:16
	s_waitcnt vmcnt(0)
	v_mul_f32_e32 v10, v10, v0
	v_add_u32_e32 v0, s9, v144
	v_or_b32_e32 v12, v0, v193
	v_ashrrev_i32_e32 v13, 31, v12
	v_lshlrev_b64 v[12:13], 11, v[12:13]
	v_lshl_add_u64 v[12:13], v[12:13], 0, s[0:1]
	v_readlane_b32 s8, v252, 2
	v_or_b32_e32 v16, v12, v145
	v_mov_b32_e32 v17, v13
	v_readlane_b32 s10, v252, 4
	v_readlane_b32 s11, v252, 5
	v_readlane_b32 s0, v254, 3
	v_readlane_b32 s1, v254, 4
	v_lshl_add_u64 v[14:15], v[16:17], 1, s[10:11]
	global_load_dwordx2 v[54:55], v[14:15], off offset:2816
	v_pk_mul_f32 v[58:59], v[88:89], v[10:11] op_sel_hi:[1,0]
	v_pk_mul_f32 v[56:57], v[90:91], v[10:11] op_sel_hi:[1,0]
	s_and_b64 vcc, exec, s[0:1]
	v_lshlrev_b32_e32 v14, 2, v145
	v_readlane_b32 s9, v252, 3
	s_cbranch_vccz .LBB0_868
	v_mov_b32_e32 v15, v1
	v_lshl_add_u64 v[60:61], v[214:215], 0, v[14:15]
	global_load_dwordx4 v[60:63], v[60:61], off
	s_waitcnt vmcnt(0)
	v_pk_mul_f32 v[58:59], v[58:59], v[60:61]
	v_pk_mul_f32 v[56:57], v[56:57], v[62:63]
